# cg sync-1 poll loop s_sleep 6
# speedup vs baseline: 1.0046x; 1.0046x over previous
.LBB0_67:
	s_sleep 6
	global_load_dword v3, v1, s[6:7] offset:32 sc1
	s_waitcnt vmcnt(0)
	v_and_b32_e32 v3, 0xffff0000, v3
	v_cmp_ne_u32_e32 vcc, v3, v2
	s_or_b64 s[10:11], vcc, s[10:11]
	s_andn2_b64 exec, exec, s[10:11]
	s_cbranch_execnz .LBB0_67
